# gate/up epilogue: each transcendental op (v_exp, v_rcp) followed by three plain VALU ops of the next block's conv (was alternating 1:1)
# speedup vs baseline: 1.0083x; 1.0028x over previous
; #define LAS __attribute__((address_space(3)))
; DI u32x2 pk4(f32x4 v) { u32x2 r; r.x = pk2(v[0], v[1]); r.y = pk2(v[2], v[3]); return r; }
;     DI void operator()(const AccT& acc, const Unit& u, int wr, int wc, int fr, int fq, LAS unsigned char* ldsx) const {
;     ...
;                 if (prompt) {
;                     if (ai | wr) { const int sai = wr ? ai : ai - 1, swr = wr ^ 1; const LAS float* hp = H + ((sai * 2 + swr) * 4 + wc) * 64 + 16 * n + 4 * fq;
;                         hm2 = *(const LAS f32x4*)hp; hm1 = *(const LAS f32x4*)(hp + 32); }
;                 } else { hm2 = *(const f32x4*)(state + (size_t)(sb * 2) * DFF + f); hm1 = *(const f32x4*)(state + (size_t)(sb * 2 + 1) * DFF + f); }
;                 f32x4 p1 = hm1, p2;
; #pragma unroll
;                 for (int j = 0; j < 4; ++j) p2[j] = fr == 1 ? hm1[j] : hm2[j];
; #pragma unroll
;                 for (int m = 0; m < 4; ++m) {
;                     const f32x4 g = acc[ai][0][m][n] * rs[ai][m];
;                     f32x4 gm1, gm2;
; #pragma unroll
;                     for (int j = 0; j < 4; ++j) {
;                         gm1[j] = __int_as_float(__builtin_amdgcn_update_dpp(__float_as_int(p1[j]), __float_as_int(g[j]), 0x111, 0xf, 0xf, false));
;                         gm2[j] = __int_as_float(__builtin_amdgcn_update_dpp(__float_as_int(p2[j]), __float_as_int(g[j]), 0x112, 0xf, 0xf, false));
;                         if (m < 3) {
;                             p1[j] = __int_as_float(__builtin_amdgcn_update_dpp(0, __float_as_int(g[j]), 0x121, 0xf, 0xf, false));
;                             p2[j] = __int_as_float(__builtin_amdgcn_update_dpp(0, __float_as_int(g[j]), 0x122, 0xf, 0xf, false)); }
;                     }
;                     const f32x4 cv = cb[n] + w0[n] * gm2 + w1[n] * gm1 + w2[n] * g;
;                     const f32x4 up = acc[ai][1][m][n] * rs[ai][m];
;                     f32x4 y;
; #pragma unroll
;                     for (int j = 0; j < 4; ++j) y[j] = cv[j] * __builtin_amdgcn_rcpf(1.f + __builtin_amdgcn_exp2f(-cv[j] * LOG2E)) * up[j];
;                     const int tok = tok0 + 128 * ai + 16 * m;
;                     bool ok = true;
;                     if (prompt && ai == 0 && m == 0) ok = (64 * wr + fr) >= 2;
;                     if (lastT) ok = ok && tok < SEQ;
;                     if (ok) *(u32x2*)(Y + ((unsigned)tok * (unsigned)DFF + (unsigned)f)) = pk4(y);
.Lgu_samp0:
	v_add_u32_e32 v213, 16, v172
	s_add_u32 s46, s54, 0xfffea000
	s_addc_u32 s47, s55, -1
	v_mul_lo_u32 v213, v213, s87
	v_cndmask_b32_e64 v160, 0, v124, s[94:95]
	v_cndmask_b32_e64 v124, v124, 0, s[94:95]
	v_cndmask_b32_e64 v164, 0, v132, s[96:97]
	v_cndmask_b32_e64 v132, v132, 0, s[96:97]
	v_cndmask_b32_e64 v161, 0, v125, s[94:95]
	v_cndmask_b32_e64 v125, v125, 0, s[94:95]
	v_cndmask_b32_e64 v165, 0, v133, s[96:97]
	v_cndmask_b32_e64 v133, v133, 0, s[96:97]
	v_cndmask_b32_e64 v162, 0, v126, s[94:95]
	v_cndmask_b32_e64 v126, v126, 0, s[94:95]
	v_cndmask_b32_e64 v166, 0, v134, s[96:97]
	v_cndmask_b32_e64 v134, v134, 0, s[96:97]
	v_cndmask_b32_e64 v163, 0, v127, s[94:95]
	v_cndmask_b32_e64 v127, v127, 0, s[94:95]
	v_cndmask_b32_e64 v167, 0, v135, s[96:97]
	v_cndmask_b32_e64 v135, v135, 0, s[96:97]
	v_add_lshl_u32 v213, v213, v216, 1
	v_pk_mul_f32 v[156:157], v[156:157], v[214:215] op_sel_hi:[1,0]
	v_pk_mul_f32 v[158:159], v[158:159], v[214:215] op_sel_hi:[1,0]
	v_pk_mul_f32 v[152:153], v[152:153], v[214:215] op_sel_hi:[1,0]
	v_pk_mul_f32 v[154:155], v[154:155], v[214:215] op_sel_hi:[1,0]
	v_pk_fma_f32 v[218:219], v[128:129], v[156:157], v[136:137]
	v_pk_fma_f32 v[220:221], v[130:131], v[158:159], v[138:139]
	v_fmac_f32_dpp v218, v156, v124 row_ror:1 row_mask:0xf bank_mask:0xf
	v_fmac_f32_dpp v219, v157, v125 row_ror:1 row_mask:0xf bank_mask:0xf
	v_fmac_f32_dpp v220, v158, v126 row_ror:1 row_mask:0xf bank_mask:0xf
	v_fmac_f32_dpp v221, v159, v127 row_ror:1 row_mask:0xf bank_mask:0xf
	v_fmac_f32_dpp v218, v156, v132 row_ror:2 row_mask:0xf bank_mask:0xf
	v_fmac_f32_dpp v219, v157, v133 row_ror:2 row_mask:0xf bank_mask:0xf
	v_fmac_f32_dpp v220, v158, v134 row_ror:2 row_mask:0xf bank_mask:0xf
	v_fmac_f32_dpp v221, v159, v135 row_ror:2 row_mask:0xf bank_mask:0xf
	s_waitcnt lgkmcnt(0)
	v_fmac_f32_e32 v218, v248, v160
	v_fmac_f32_e32 v219, v249, v161
	v_fmac_f32_e32 v220, v250, v162
	v_fmac_f32_e32 v221, v251, v163
	v_fmac_f32_dpp v218, v248, v164 row_ror:14 row_mask:0xf bank_mask:0xf
	v_fmac_f32_dpp v219, v249, v165 row_ror:14 row_mask:0xf bank_mask:0xf
	v_fmac_f32_dpp v220, v250, v166 row_ror:14 row_mask:0xf bank_mask:0xf
	v_fmac_f32_dpp v221, v251, v167 row_ror:14 row_mask:0xf bank_mask:0xf
	v_pk_mul_f32 v[204:205], v[218:219], v[184:185] op_sel:[0,1] op_sel_hi:[1,1]
	v_pk_mul_f32 v[206:207], v[220:221], v[184:185] op_sel:[0,1] op_sel_hi:[1,1]
	v_exp_f32_e32 v204, v204
	v_pk_mul_f32 v[148:149], v[148:149], v[210:211] op_sel_hi:[1,0]
	v_pk_mul_f32 v[150:151], v[150:151], v[210:211] op_sel_hi:[1,0]
	v_pk_mul_f32 v[144:145], v[144:145], v[210:211] op_sel_hi:[1,0]
	v_exp_f32_e32 v205, v205
	v_pk_mul_f32 v[146:147], v[146:147], v[210:211] op_sel_hi:[1,0]
	v_pk_fma_f32 v[222:223], v[128:129], v[148:149], v[136:137]
	v_pk_fma_f32 v[224:225], v[130:131], v[150:151], v[138:139]
	v_exp_f32_e32 v206, v206
	v_fmac_f32_dpp v222, v148, v124 row_ror:1 row_mask:0xf bank_mask:0xf
	v_fmac_f32_dpp v223, v149, v125 row_ror:1 row_mask:0xf bank_mask:0xf
	v_fmac_f32_dpp v224, v150, v126 row_ror:1 row_mask:0xf bank_mask:0xf
	v_exp_f32_e32 v207, v207
	v_fmac_f32_dpp v225, v151, v127 row_ror:1 row_mask:0xf bank_mask:0xf
	v_fmac_f32_dpp v222, v148, v132 row_ror:2 row_mask:0xf bank_mask:0xf
	v_fmac_f32_dpp v223, v149, v133 row_ror:2 row_mask:0xf bank_mask:0xf
	v_pk_add_f32 v[204:205], v[204:205], 1.0 op_sel_hi:[1,0]
	v_pk_add_f32 v[206:207], v[206:207], 1.0 op_sel_hi:[1,0]
	v_rcp_f32_e32 v204, v204
	v_fmac_f32_dpp v224, v150, v134 row_ror:2 row_mask:0xf bank_mask:0xf
	v_fmac_f32_dpp v225, v151, v135 row_ror:2 row_mask:0xf bank_mask:0xf
	v_fmac_f32_dpp v222, v156, v160 row_ror:1 row_mask:0xf bank_mask:0xf
	v_rcp_f32_e32 v205, v205
	v_fmac_f32_dpp v223, v157, v161 row_ror:1 row_mask:0xf bank_mask:0xf
	v_fmac_f32_dpp v224, v158, v162 row_ror:1 row_mask:0xf bank_mask:0xf
	v_fmac_f32_dpp v225, v159, v163 row_ror:1 row_mask:0xf bank_mask:0xf
	v_rcp_f32_e32 v206, v206
	v_fmac_f32_dpp v222, v156, v164 row_ror:2 row_mask:0xf bank_mask:0xf
	v_fmac_f32_dpp v223, v157, v165 row_ror:2 row_mask:0xf bank_mask:0xf
	v_fmac_f32_dpp v224, v158, v166 row_ror:2 row_mask:0xf bank_mask:0xf
	v_rcp_f32_e32 v207, v207
	v_fmac_f32_dpp v225, v159, v167 row_ror:2 row_mask:0xf bank_mask:0xf
	v_pk_mul_f32 v[218:219], v[218:219], v[204:205]
	v_pk_mul_f32 v[220:221], v[220:221], v[206:207]
	v_pk_mul_f32 v[152:153], v[152:153], v[218:219]
	v_pk_mul_f32 v[154:155], v[154:155], v[220:221]
	v_cvt_pk_bf16_f32 v152, v152, v153
	v_cvt_pk_bf16_f32 v153, v154, v155
	s_and_saveexec_b64 s[28:29], s[60:61]
	global_store_dwordx2 v213, v[152:153], s[46:47]
	s_mov_b64 exec, s[28:29]
	s_add_u32 s46, s46, 0x16000
	s_addc_u32 s47, s47, 0
	v_pk_mul_f32 v[204:205], v[222:223], v[184:185] op_sel:[0,1] op_sel_hi:[1,1]
	v_pk_mul_f32 v[206:207], v[224:225], v[184:185] op_sel:[0,1] op_sel_hi:[1,1]
	v_exp_f32_e32 v204, v204
	v_pk_mul_f32 v[140:141], v[140:141], v[208:209] op_sel_hi:[1,0]
	v_pk_mul_f32 v[142:143], v[142:143], v[208:209] op_sel_hi:[1,0]
	v_pk_mul_f32 v[120:121], v[120:121], v[208:209] op_sel_hi:[1,0]
	v_exp_f32_e32 v205, v205
	v_pk_mul_f32 v[122:123], v[122:123], v[208:209] op_sel_hi:[1,0]
	v_pk_fma_f32 v[218:219], v[128:129], v[140:141], v[136:137]
	v_pk_fma_f32 v[220:221], v[130:131], v[142:143], v[138:139]
	v_exp_f32_e32 v206, v206
	v_fmac_f32_dpp v218, v140, v124 row_ror:1 row_mask:0xf bank_mask:0xf
	v_fmac_f32_dpp v219, v141, v125 row_ror:1 row_mask:0xf bank_mask:0xf
	v_fmac_f32_dpp v220, v142, v126 row_ror:1 row_mask:0xf bank_mask:0xf
	v_exp_f32_e32 v207, v207
	v_fmac_f32_dpp v221, v143, v127 row_ror:1 row_mask:0xf bank_mask:0xf
	v_fmac_f32_dpp v218, v140, v132 row_ror:2 row_mask:0xf bank_mask:0xf
; #define LAS __attribute__((address_space(3)))
; DI u32x2 pk4(f32x4 v) { u32x2 r; r.x = pk2(v[0], v[1]); r.y = pk2(v[2], v[3]); return r; }
;     DI void operator()(const AccT& acc, const Unit& u, int wr, int wc, int fr, int fq, LAS unsigned char* ldsx) const {
;     ...
;                 if (prompt) {
;                     if (ai | wr) { const int sai = wr ? ai : ai - 1, swr = wr ^ 1; const LAS float* hp = H + ((sai * 2 + swr) * 4 + wc) * 64 + 16 * n + 4 * fq;
;                         hm2 = *(const LAS f32x4*)hp; hm1 = *(const LAS f32x4*)(hp + 32); }
;                 } else { hm2 = *(const f32x4*)(state + (size_t)(sb * 2) * DFF + f); hm1 = *(const f32x4*)(state + (size_t)(sb * 2 + 1) * DFF + f); }
;                 f32x4 p1 = hm1, p2;
; #pragma unroll
;                 for (int j = 0; j < 4; ++j) p2[j] = fr == 1 ? hm1[j] : hm2[j];
; #pragma unroll
;                 for (int m = 0; m < 4; ++m) {
;                     const f32x4 g = acc[ai][0][m][n] * rs[ai][m];
;                     f32x4 gm1, gm2;
; #pragma unroll
;                     for (int j = 0; j < 4; ++j) {
;                         gm1[j] = __int_as_float(__builtin_amdgcn_update_dpp(__float_as_int(p1[j]), __float_as_int(g[j]), 0x111, 0xf, 0xf, false));
;                         gm2[j] = __int_as_float(__builtin_amdgcn_update_dpp(__float_as_int(p2[j]), __float_as_int(g[j]), 0x112, 0xf, 0xf, false));
;                         if (m < 3) {
;                             p1[j] = __int_as_float(__builtin_amdgcn_update_dpp(0, __float_as_int(g[j]), 0x121, 0xf, 0xf, false));
;                             p2[j] = __int_as_float(__builtin_amdgcn_update_dpp(0, __float_as_int(g[j]), 0x122, 0xf, 0xf, false)); }
;                     }
;                     const f32x4 cv = cb[n] + w0[n] * gm2 + w1[n] * gm1 + w2[n] * g;
;                     const f32x4 up = acc[ai][1][m][n] * rs[ai][m];
;                     f32x4 y;
; #pragma unroll
;                     for (int j = 0; j < 4; ++j) y[j] = cv[j] * __builtin_amdgcn_rcpf(1.f + __builtin_amdgcn_exp2f(-cv[j] * LOG2E)) * up[j];
;                     const int tok = tok0 + 128 * ai + 16 * m;
;                     bool ok = true;
;                     if (prompt && ai == 0 && m == 0) ok = (64 * wr + fr) >= 2;
;                     if (lastT) ok = ok && tok < SEQ;
;                     if (ok) *(u32x2*)(Y + ((unsigned)tok * (unsigned)DFF + (unsigned)f)) = pk4(y);
	v_fmac_f32_dpp v219, v141, v133 row_ror:2 row_mask:0xf bank_mask:0xf
	v_pk_add_f32 v[204:205], v[204:205], 1.0 op_sel_hi:[1,0]
	v_pk_add_f32 v[206:207], v[206:207], 1.0 op_sel_hi:[1,0]
	v_rcp_f32_e32 v204, v204
	v_fmac_f32_dpp v220, v142, v134 row_ror:2 row_mask:0xf bank_mask:0xf
	v_fmac_f32_dpp v221, v143, v135 row_ror:2 row_mask:0xf bank_mask:0xf
	v_fmac_f32_dpp v218, v148, v160 row_ror:1 row_mask:0xf bank_mask:0xf
	v_rcp_f32_e32 v205, v205
	v_fmac_f32_dpp v219, v149, v161 row_ror:1 row_mask:0xf bank_mask:0xf
	v_fmac_f32_dpp v220, v150, v162 row_ror:1 row_mask:0xf bank_mask:0xf
	v_fmac_f32_dpp v221, v151, v163 row_ror:1 row_mask:0xf bank_mask:0xf
	v_rcp_f32_e32 v206, v206
	v_fmac_f32_dpp v218, v148, v164 row_ror:2 row_mask:0xf bank_mask:0xf
	v_fmac_f32_dpp v219, v149, v165 row_ror:2 row_mask:0xf bank_mask:0xf
	v_fmac_f32_dpp v220, v150, v166 row_ror:2 row_mask:0xf bank_mask:0xf
	v_rcp_f32_e32 v207, v207
	v_fmac_f32_dpp v221, v151, v167 row_ror:2 row_mask:0xf bank_mask:0xf
	v_pk_mul_f32 v[222:223], v[222:223], v[204:205]
	v_pk_mul_f32 v[224:225], v[224:225], v[206:207]
	v_pk_mul_f32 v[144:145], v[144:145], v[222:223]
	v_pk_mul_f32 v[146:147], v[146:147], v[224:225]
	v_cvt_pk_bf16_f32 v144, v144, v145
	v_cvt_pk_bf16_f32 v145, v146, v147
	s_and_saveexec_b64 s[28:29], s[62:63]
	global_store_dwordx2 v213, v[144:145], s[46:47]
	s_mov_b64 exec, s[28:29]
	s_add_u32 s46, s46, 0x16000
	s_addc_u32 s47, s47, 0
	v_pk_mul_f32 v[204:205], v[218:219], v[184:185] op_sel:[0,1] op_sel_hi:[1,1]
	v_pk_mul_f32 v[206:207], v[220:221], v[184:185] op_sel:[0,1] op_sel_hi:[1,1]
	v_exp_f32_e32 v204, v204
	v_pk_mul_f32 v[116:117], v[116:117], v[202:203] op_sel_hi:[1,0]
	v_pk_mul_f32 v[118:119], v[118:119], v[202:203] op_sel_hi:[1,0]
	v_pk_mul_f32 v[112:113], v[112:113], v[202:203] op_sel_hi:[1,0]
	v_exp_f32_e32 v205, v205
	v_pk_mul_f32 v[114:115], v[114:115], v[202:203] op_sel_hi:[1,0]
	v_pk_fma_f32 v[222:223], v[128:129], v[116:117], v[136:137]
	v_pk_fma_f32 v[224:225], v[130:131], v[118:119], v[138:139]
	v_exp_f32_e32 v206, v206
	v_fmac_f32_dpp v222, v116, v124 row_ror:1 row_mask:0xf bank_mask:0xf
	v_fmac_f32_dpp v223, v117, v125 row_ror:1 row_mask:0xf bank_mask:0xf
	v_fmac_f32_dpp v224, v118, v126 row_ror:1 row_mask:0xf bank_mask:0xf
	v_exp_f32_e32 v207, v207
	v_fmac_f32_dpp v225, v119, v127 row_ror:1 row_mask:0xf bank_mask:0xf
	v_fmac_f32_dpp v222, v116, v132 row_ror:2 row_mask:0xf bank_mask:0xf
	v_fmac_f32_dpp v223, v117, v133 row_ror:2 row_mask:0xf bank_mask:0xf
	v_pk_add_f32 v[204:205], v[204:205], 1.0 op_sel_hi:[1,0]
	v_pk_add_f32 v[206:207], v[206:207], 1.0 op_sel_hi:[1,0]
	v_rcp_f32_e32 v204, v204
	v_fmac_f32_dpp v224, v118, v134 row_ror:2 row_mask:0xf bank_mask:0xf
	v_fmac_f32_dpp v225, v119, v135 row_ror:2 row_mask:0xf bank_mask:0xf
	v_fmac_f32_dpp v222, v140, v160 row_ror:1 row_mask:0xf bank_mask:0xf
	v_rcp_f32_e32 v205, v205
	v_fmac_f32_dpp v223, v141, v161 row_ror:1 row_mask:0xf bank_mask:0xf
	v_fmac_f32_dpp v224, v142, v162 row_ror:1 row_mask:0xf bank_mask:0xf
	v_fmac_f32_dpp v225, v143, v163 row_ror:1 row_mask:0xf bank_mask:0xf
	v_rcp_f32_e32 v206, v206
	v_fmac_f32_dpp v222, v140, v164 row_ror:2 row_mask:0xf bank_mask:0xf
	v_fmac_f32_dpp v223, v141, v165 row_ror:2 row_mask:0xf bank_mask:0xf
	v_fmac_f32_dpp v224, v142, v166 row_ror:2 row_mask:0xf bank_mask:0xf
	v_rcp_f32_e32 v207, v207
	v_fmac_f32_dpp v225, v143, v167 row_ror:2 row_mask:0xf bank_mask:0xf
	v_pk_mul_f32 v[218:219], v[218:219], v[204:205]
	v_pk_mul_f32 v[220:221], v[220:221], v[206:207]
	v_pk_mul_f32 v[120:121], v[120:121], v[218:219]
	v_pk_mul_f32 v[122:123], v[122:123], v[220:221]
	v_cvt_pk_bf16_f32 v120, v120, v121
	v_cvt_pk_bf16_f32 v121, v122, v123
	s_and_saveexec_b64 s[28:29], s[64:65]
	global_store_dwordx2 v213, v[120:121], s[46:47]
	s_mov_b64 exec, s[28:29]
	s_add_u32 s46, s46, 0x16000
	s_addc_u32 s47, s47, 0
	v_pk_mul_f32 v[204:205], v[222:223], v[184:185] op_sel:[0,1] op_sel_hi:[1,1]
	v_pk_mul_f32 v[206:207], v[224:225], v[184:185] op_sel:[0,1] op_sel_hi:[1,1]
	v_exp_f32_e32 v204, v204
	v_pk_mul_f32 v[108:109], v[108:109], v[200:201] op_sel_hi:[1,0]
	v_pk_mul_f32 v[110:111], v[110:111], v[200:201] op_sel_hi:[1,0]
	v_pk_mul_f32 v[104:105], v[104:105], v[200:201] op_sel_hi:[1,0]
	v_exp_f32_e32 v205, v205
	v_pk_mul_f32 v[106:107], v[106:107], v[200:201] op_sel_hi:[1,0]
	v_pk_fma_f32 v[218:219], v[128:129], v[108:109], v[136:137]
	v_pk_fma_f32 v[220:221], v[130:131], v[110:111], v[138:139]
	v_exp_f32_e32 v206, v206
	v_fmac_f32_dpp v218, v108, v124 row_ror:1 row_mask:0xf bank_mask:0xf
	v_fmac_f32_dpp v219, v109, v125 row_ror:1 row_mask:0xf bank_mask:0xf
	v_fmac_f32_dpp v220, v110, v126 row_ror:1 row_mask:0xf bank_mask:0xf
	v_exp_f32_e32 v207, v207
	v_fmac_f32_dpp v221, v111, v127 row_ror:1 row_mask:0xf bank_mask:0xf
	v_fmac_f32_dpp v218, v108, v132 row_ror:2 row_mask:0xf bank_mask:0xf
	v_fmac_f32_dpp v219, v109, v133 row_ror:2 row_mask:0xf bank_mask:0xf
	v_pk_add_f32 v[204:205], v[204:205], 1.0 op_sel_hi:[1,0]
	v_pk_add_f32 v[206:207], v[206:207], 1.0 op_sel_hi:[1,0]
	v_rcp_f32_e32 v204, v204
	v_fmac_f32_dpp v220, v110, v134 row_ror:2 row_mask:0xf bank_mask:0xf
	v_fmac_f32_dpp v221, v111, v135 row_ror:2 row_mask:0xf bank_mask:0xf
	v_fmac_f32_dpp v218, v248, v160 row_ror:12 row_mask:0xf bank_mask:0xf
	v_rcp_f32_e32 v205, v205
	v_fmac_f32_dpp v219, v249, v161 row_ror:12 row_mask:0xf bank_mask:0xf
	v_fmac_f32_dpp v220, v250, v162 row_ror:12 row_mask:0xf bank_mask:0xf
	v_fmac_f32_dpp v221, v251, v163 row_ror:12 row_mask:0xf bank_mask:0xf
	v_rcp_f32_e32 v206, v206
	v_fmac_f32_dpp v218, v248, v164 row_ror:10 row_mask:0xf bank_mask:0xf
	v_fmac_f32_dpp v219, v249, v165 row_ror:10 row_mask:0xf bank_mask:0xf
; #define LAS __attribute__((address_space(3)))
; DI u32x2 pk4(f32x4 v) { u32x2 r; r.x = pk2(v[0], v[1]); r.y = pk2(v[2], v[3]); return r; }
;     DI void operator()(const AccT& acc, const Unit& u, int wr, int wc, int fr, int fq, LAS unsigned char* ldsx) const {
;     ...
;                 if (prompt) {
;                     if (ai | wr) { const int sai = wr ? ai : ai - 1, swr = wr ^ 1; const LAS float* hp = H + ((sai * 2 + swr) * 4 + wc) * 64 + 16 * n + 4 * fq;
;                         hm2 = *(const LAS f32x4*)hp; hm1 = *(const LAS f32x4*)(hp + 32); }
;                 } else { hm2 = *(const f32x4*)(state + (size_t)(sb * 2) * DFF + f); hm1 = *(const f32x4*)(state + (size_t)(sb * 2 + 1) * DFF + f); }
;                 f32x4 p1 = hm1, p2;
; #pragma unroll
;                 for (int j = 0; j < 4; ++j) p2[j] = fr == 1 ? hm1[j] : hm2[j];
; #pragma unroll
;                 for (int m = 0; m < 4; ++m) {
;                     const f32x4 g = acc[ai][0][m][n] * rs[ai][m];
;                     f32x4 gm1, gm2;
; #pragma unroll
;                     for (int j = 0; j < 4; ++j) {
;                         gm1[j] = __int_as_float(__builtin_amdgcn_update_dpp(__float_as_int(p1[j]), __float_as_int(g[j]), 0x111, 0xf, 0xf, false));
;                         gm2[j] = __int_as_float(__builtin_amdgcn_update_dpp(__float_as_int(p2[j]), __float_as_int(g[j]), 0x112, 0xf, 0xf, false));
;                         if (m < 3) {
;                             p1[j] = __int_as_float(__builtin_amdgcn_update_dpp(0, __float_as_int(g[j]), 0x121, 0xf, 0xf, false));
;                             p2[j] = __int_as_float(__builtin_amdgcn_update_dpp(0, __float_as_int(g[j]), 0x122, 0xf, 0xf, false)); }
;                     }
;                     const f32x4 cv = cb[n] + w0[n] * gm2 + w1[n] * gm1 + w2[n] * g;
;                     const f32x4 up = acc[ai][1][m][n] * rs[ai][m];
;                     f32x4 y;
; #pragma unroll
;                     for (int j = 0; j < 4; ++j) y[j] = cv[j] * __builtin_amdgcn_rcpf(1.f + __builtin_amdgcn_exp2f(-cv[j] * LOG2E)) * up[j];
;                     const int tok = tok0 + 128 * ai + 16 * m;
;                     bool ok = true;
;                     if (prompt && ai == 0 && m == 0) ok = (64 * wr + fr) >= 2;
;                     if (lastT) ok = ok && tok < SEQ;
;                     if (ok) *(u32x2*)(Y + ((unsigned)tok * (unsigned)DFF + (unsigned)f)) = pk4(y);
	v_fmac_f32_dpp v220, v250, v166 row_ror:10 row_mask:0xf bank_mask:0xf
	v_rcp_f32_e32 v207, v207
	v_fmac_f32_dpp v221, v251, v167 row_ror:10 row_mask:0xf bank_mask:0xf
	v_pk_mul_f32 v[222:223], v[222:223], v[204:205]
	v_pk_mul_f32 v[224:225], v[224:225], v[206:207]
	v_pk_mul_f32 v[112:113], v[112:113], v[222:223]
	v_pk_mul_f32 v[114:115], v[114:115], v[224:225]
	v_cvt_pk_bf16_f32 v112, v112, v113
	v_cvt_pk_bf16_f32 v113, v114, v115
	s_and_saveexec_b64 s[28:29], s[66:67]
	global_store_dwordx2 v213, v[112:113], s[46:47]
	s_mov_b64 exec, s[28:29]
	s_add_u32 s46, s46, 0x6e000
	s_addc_u32 s47, s47, 0
	v_pk_mul_f32 v[204:205], v[218:219], v[184:185] op_sel:[0,1] op_sel_hi:[1,1]
	v_pk_mul_f32 v[206:207], v[220:221], v[184:185] op_sel:[0,1] op_sel_hi:[1,1]
	v_exp_f32_e32 v204, v204
	v_pk_mul_f32 v[100:101], v[100:101], v[192:193] op_sel_hi:[1,0]
	v_pk_mul_f32 v[102:103], v[102:103], v[192:193] op_sel_hi:[1,0]
	v_pk_mul_f32 v[96:97], v[96:97], v[192:193] op_sel_hi:[1,0]
	v_exp_f32_e32 v205, v205
	v_pk_mul_f32 v[98:99], v[98:99], v[192:193] op_sel_hi:[1,0]
	v_pk_fma_f32 v[222:223], v[128:129], v[100:101], v[136:137]
	v_pk_fma_f32 v[224:225], v[130:131], v[102:103], v[138:139]
	v_exp_f32_e32 v206, v206
	v_fmac_f32_dpp v222, v100, v124 row_ror:1 row_mask:0xf bank_mask:0xf
	v_fmac_f32_dpp v223, v101, v125 row_ror:1 row_mask:0xf bank_mask:0xf
	v_fmac_f32_dpp v224, v102, v126 row_ror:1 row_mask:0xf bank_mask:0xf
	v_exp_f32_e32 v207, v207
	v_fmac_f32_dpp v225, v103, v127 row_ror:1 row_mask:0xf bank_mask:0xf
	v_fmac_f32_dpp v222, v100, v132 row_ror:2 row_mask:0xf bank_mask:0xf
	v_fmac_f32_dpp v223, v101, v133 row_ror:2 row_mask:0xf bank_mask:0xf
	v_pk_add_f32 v[204:205], v[204:205], 1.0 op_sel_hi:[1,0]
	v_pk_add_f32 v[206:207], v[206:207], 1.0 op_sel_hi:[1,0]
	v_rcp_f32_e32 v204, v204
	v_fmac_f32_dpp v224, v102, v134 row_ror:2 row_mask:0xf bank_mask:0xf
	v_fmac_f32_dpp v225, v103, v135 row_ror:2 row_mask:0xf bank_mask:0xf
	v_fmac_f32_dpp v222, v108, v160 row_ror:1 row_mask:0xf bank_mask:0xf
	v_rcp_f32_e32 v205, v205
	v_fmac_f32_dpp v223, v109, v161 row_ror:1 row_mask:0xf bank_mask:0xf
	v_fmac_f32_dpp v224, v110, v162 row_ror:1 row_mask:0xf bank_mask:0xf
	v_fmac_f32_dpp v225, v111, v163 row_ror:1 row_mask:0xf bank_mask:0xf
	v_rcp_f32_e32 v206, v206
	v_fmac_f32_dpp v222, v108, v164 row_ror:2 row_mask:0xf bank_mask:0xf
	v_fmac_f32_dpp v223, v109, v165 row_ror:2 row_mask:0xf bank_mask:0xf
	v_fmac_f32_dpp v224, v110, v166 row_ror:2 row_mask:0xf bank_mask:0xf
	v_rcp_f32_e32 v207, v207
	v_fmac_f32_dpp v225, v111, v167 row_ror:2 row_mask:0xf bank_mask:0xf
	v_pk_mul_f32 v[218:219], v[218:219], v[204:205]
	v_pk_mul_f32 v[220:221], v[220:221], v[206:207]
	v_pk_mul_f32 v[104:105], v[104:105], v[218:219]
	v_pk_mul_f32 v[106:107], v[106:107], v[220:221]
	v_cvt_pk_bf16_f32 v104, v104, v105
	v_cvt_pk_bf16_f32 v105, v106, v107
	s_and_saveexec_b64 s[28:29], s[68:69]
	global_store_dwordx2 v213, v[104:105], s[46:47]
	s_mov_b64 exec, s[28:29]
	s_add_u32 s46, s46, 0x16000
	s_addc_u32 s47, s47, 0
	v_pk_mul_f32 v[204:205], v[222:223], v[184:185] op_sel:[0,1] op_sel_hi:[1,1]
	v_pk_mul_f32 v[206:207], v[224:225], v[184:185] op_sel:[0,1] op_sel_hi:[1,1]
	v_exp_f32_e32 v204, v204
	v_pk_mul_f32 v[92:93], v[92:93], v[190:191] op_sel_hi:[1,0]
	v_pk_mul_f32 v[94:95], v[94:95], v[190:191] op_sel_hi:[1,0]
	v_pk_mul_f32 v[88:89], v[88:89], v[190:191] op_sel_hi:[1,0]
	v_exp_f32_e32 v205, v205
	v_pk_mul_f32 v[90:91], v[90:91], v[190:191] op_sel_hi:[1,0]
	v_pk_fma_f32 v[218:219], v[128:129], v[92:93], v[136:137]
	v_pk_fma_f32 v[220:221], v[130:131], v[94:95], v[138:139]
	v_exp_f32_e32 v206, v206
	v_fmac_f32_dpp v218, v92, v124 row_ror:1 row_mask:0xf bank_mask:0xf
	v_fmac_f32_dpp v219, v93, v125 row_ror:1 row_mask:0xf bank_mask:0xf
	v_fmac_f32_dpp v220, v94, v126 row_ror:1 row_mask:0xf bank_mask:0xf
	v_exp_f32_e32 v207, v207
	v_fmac_f32_dpp v221, v95, v127 row_ror:1 row_mask:0xf bank_mask:0xf
	v_fmac_f32_dpp v218, v92, v132 row_ror:2 row_mask:0xf bank_mask:0xf
	v_fmac_f32_dpp v219, v93, v133 row_ror:2 row_mask:0xf bank_mask:0xf
	v_pk_add_f32 v[204:205], v[204:205], 1.0 op_sel_hi:[1,0]
	v_pk_add_f32 v[206:207], v[206:207], 1.0 op_sel_hi:[1,0]
	v_rcp_f32_e32 v204, v204
	v_fmac_f32_dpp v220, v94, v134 row_ror:2 row_mask:0xf bank_mask:0xf
	v_fmac_f32_dpp v221, v95, v135 row_ror:2 row_mask:0xf bank_mask:0xf
	v_fmac_f32_dpp v218, v100, v160 row_ror:1 row_mask:0xf bank_mask:0xf
	v_rcp_f32_e32 v205, v205
	v_fmac_f32_dpp v219, v101, v161 row_ror:1 row_mask:0xf bank_mask:0xf
	v_fmac_f32_dpp v220, v102, v162 row_ror:1 row_mask:0xf bank_mask:0xf
	v_fmac_f32_dpp v221, v103, v163 row_ror:1 row_mask:0xf bank_mask:0xf
	v_rcp_f32_e32 v206, v206
	v_fmac_f32_dpp v218, v100, v164 row_ror:2 row_mask:0xf bank_mask:0xf
	v_fmac_f32_dpp v219, v101, v165 row_ror:2 row_mask:0xf bank_mask:0xf
	v_fmac_f32_dpp v220, v102, v166 row_ror:2 row_mask:0xf bank_mask:0xf
	v_rcp_f32_e32 v207, v207
	v_fmac_f32_dpp v221, v103, v167 row_ror:2 row_mask:0xf bank_mask:0xf
	v_pk_mul_f32 v[222:223], v[222:223], v[204:205]
	v_pk_mul_f32 v[224:225], v[224:225], v[206:207]
	v_pk_mul_f32 v[96:97], v[96:97], v[222:223]
	v_pk_mul_f32 v[98:99], v[98:99], v[224:225]
	v_cvt_pk_bf16_f32 v96, v96, v97
	v_cvt_pk_bf16_f32 v97, v98, v99
	s_and_saveexec_b64 s[28:29], s[70:71]
	global_store_dwordx2 v213, v[96:97], s[46:47]
	s_mov_b64 exec, s[28:29]
	s_add_u32 s46, s46, 0x16000
	s_addc_u32 s47, s47, 0
	v_pk_mul_f32 v[204:205], v[218:219], v[184:185] op_sel:[0,1] op_sel_hi:[1,1]
	v_pk_mul_f32 v[206:207], v[220:221], v[184:185] op_sel:[0,1] op_sel_hi:[1,1]
	v_exp_f32_e32 v204, v204
	v_pk_mul_f32 v[84:85], v[84:85], v[184:185] op_sel_hi:[1,0]
; #define LAS __attribute__((address_space(3)))
;     DI void operator()(const AccT& acc, const Unit& u, int wr, int wc, int fr, int fq, LAS unsigned char* ldsx) const {
;     ...
;         for (int n = 0; n < 2; ++n) { const int f = u.pn * 128 + wc * 32 + 16 * n + 4 * fq;
;             w0[n] = *(const f32x4*)(convw + f); w1[n] = *(const f32x4*)(convw + DFF + f); w2[n] = *(const f32x4*)(convw + 2 * DFF + f); cb[n] = *(const f32x4*)(convb + f); }
;         float rs[2][4];
; #pragma unroll
;         for (int ai = 0; ai < 2; ++ai)
; #pragma unroll
;             for (int m = 0; m < 4; ++m) { const int tok = tok0 + 128 * ai + 16 * m; const bool ok = tok >= 0 && tok < (prompt ? SEQ : MTOK);
;                 rs[ai][m] = ok ? rsqrtf(sumsq[ok ? tok : 0] * (1.f / DM) + EPS) : 0.f; }
;         if (prompt) {
;             if (fr >= 14) {
; #pragma unroll
;                 for (int ai = 0; ai < 2; ++ai)
; #pragma unroll
;                     for (int n = 0; n < 2; ++n) *(LAS f32x4*)(H + ((ai * 2 + wr) * 4 + wc) * 64 + (fr - 14) * 32 + 16 * n + 4 * fq) = acc[ai][0][3][n] * rs[ai][3];
;             }
;             asm volatile("s_waitcnt lgkmcnt(0)" ::: "memory"); __builtin_amdgcn_s_barrier(); asm volatile("" ::: "memory");
;         }
; #pragma unroll
;         for (int n = 0; n < 2; ++n) {
;             const int f = u.pn * 128 + wc * 32 + 16 * n + 4 * fq;
; #pragma unroll
;             for (int ai = 0; ai < 2; ++ai) {
;                 f32x4 hm1 = {0.f, 0.f, 0.f, 0.f}, hm2 = {0.f, 0.f, 0.f, 0.f};
;                 const int sb = 4 * (T - GU_PT) + 2 * ai + wr;
;                 if (prompt) {
;                     if (ai | wr) { const int sai = wr ? ai : ai - 1, swr = wr ^ 1; const LAS float* hp = H + ((sai * 2 + swr) * 4 + wc) * 64 + 16 * n + 4 * fq;
;                         hm2 = *(const LAS f32x4*)hp; hm1 = *(const LAS f32x4*)(hp + 32); }
;                 } else { hm2 = *(const f32x4*)(state + (size_t)(sb * 2) * DFF + f); hm1 = *(const f32x4*)(state + (size_t)(sb * 2 + 1) * DFF + f); }
;                 f32x4 p1 = hm1, p2;
; #pragma unroll
;                 for (int j = 0; j < 4; ++j) p2[j] = fr == 1 ? hm1[j] : hm2[j];
; #pragma unroll
;                 for (int m = 0; m < 4; ++m) {
;                     const f32x4 g = acc[ai][0][m][n] * rs[ai][m];
;                     f32x4 gm1, gm2;
; #pragma unroll
;                     for (int j = 0; j < 4; ++j) {
	v_pk_mul_f32 v[86:87], v[86:87], v[184:185] op_sel_hi:[1,0]
	v_pk_mul_f32 v[80:81], v[80:81], v[184:185] op_sel_hi:[1,0]
	v_exp_f32_e32 v205, v205
	v_pk_mul_f32 v[82:83], v[82:83], v[184:185] op_sel_hi:[1,0]
	v_pk_fma_f32 v[222:223], v[128:129], v[84:85], v[136:137]
	v_pk_fma_f32 v[224:225], v[130:131], v[86:87], v[138:139]
	v_exp_f32_e32 v206, v206
	v_fmac_f32_dpp v222, v84, v124 row_ror:1 row_mask:0xf bank_mask:0xf
	v_fmac_f32_dpp v223, v85, v125 row_ror:1 row_mask:0xf bank_mask:0xf
	v_fmac_f32_dpp v224, v86, v126 row_ror:1 row_mask:0xf bank_mask:0xf
	v_exp_f32_e32 v207, v207
	v_fmac_f32_dpp v225, v87, v127 row_ror:1 row_mask:0xf bank_mask:0xf
	v_fmac_f32_dpp v222, v84, v132 row_ror:2 row_mask:0xf bank_mask:0xf
	v_fmac_f32_dpp v223, v85, v133 row_ror:2 row_mask:0xf bank_mask:0xf
	v_pk_add_f32 v[204:205], v[204:205], 1.0 op_sel_hi:[1,0]
	v_pk_add_f32 v[206:207], v[206:207], 1.0 op_sel_hi:[1,0]
	v_rcp_f32_e32 v204, v204
	v_fmac_f32_dpp v224, v86, v134 row_ror:2 row_mask:0xf bank_mask:0xf
	v_fmac_f32_dpp v225, v87, v135 row_ror:2 row_mask:0xf bank_mask:0xf
	v_fmac_f32_dpp v222, v92, v160 row_ror:1 row_mask:0xf bank_mask:0xf
	v_rcp_f32_e32 v205, v205
	v_fmac_f32_dpp v223, v93, v161 row_ror:1 row_mask:0xf bank_mask:0xf
	v_fmac_f32_dpp v224, v94, v162 row_ror:1 row_mask:0xf bank_mask:0xf
	v_fmac_f32_dpp v225, v95, v163 row_ror:1 row_mask:0xf bank_mask:0xf
	v_rcp_f32_e32 v206, v206
	v_fmac_f32_dpp v222, v92, v164 row_ror:2 row_mask:0xf bank_mask:0xf
	v_fmac_f32_dpp v223, v93, v165 row_ror:2 row_mask:0xf bank_mask:0xf
	v_fmac_f32_dpp v224, v94, v166 row_ror:2 row_mask:0xf bank_mask:0xf
	v_rcp_f32_e32 v207, v207
	v_fmac_f32_dpp v225, v95, v167 row_ror:2 row_mask:0xf bank_mask:0xf
	v_pk_mul_f32 v[218:219], v[218:219], v[204:205]
	v_pk_mul_f32 v[220:221], v[220:221], v[206:207]
	v_pk_mul_f32 v[88:89], v[88:89], v[218:219]
	v_pk_mul_f32 v[90:91], v[90:91], v[220:221]
	v_cvt_pk_bf16_f32 v88, v88, v89
	v_cvt_pk_bf16_f32 v89, v90, v91
	s_and_saveexec_b64 s[28:29], s[72:73]
	global_store_dwordx2 v213, v[88:89], s[46:47]
	s_mov_b64 exec, s[28:29]
	s_add_u32 s46, s46, 0x16000
	s_addc_u32 s47, s47, 0
	v_cndmask_b32_e64 v160, 0, v48, s[94:95]
	v_cndmask_b32_e64 v48, v48, 0, s[94:95]
	v_cndmask_b32_e64 v164, 0, v44, s[96:97]
	v_cndmask_b32_e64 v44, v44, 0, s[96:97]
	v_cndmask_b32_e64 v161, 0, v49, s[94:95]
	v_cndmask_b32_e64 v49, v49, 0, s[94:95]
	v_cndmask_b32_e64 v165, 0, v45, s[96:97]
	v_cndmask_b32_e64 v45, v45, 0, s[96:97]
	v_cndmask_b32_e64 v162, 0, v50, s[94:95]
	v_cndmask_b32_e64 v50, v50, 0, s[94:95]
	v_cndmask_b32_e64 v166, 0, v46, s[96:97]
	v_cndmask_b32_e64 v46, v46, 0, s[96:97]
	v_cndmask_b32_e64 v163, 0, v51, s[94:95]
	v_cndmask_b32_e64 v51, v51, 0, s[94:95]
	v_cndmask_b32_e64 v167, 0, v47, s[96:97]
	v_cndmask_b32_e64 v47, v47, 0, s[96:97]
	v_pk_mul_f32 v[204:205], v[222:223], v[184:185] op_sel:[0,1] op_sel_hi:[1,1]
	v_pk_mul_f32 v[206:207], v[224:225], v[184:185] op_sel:[0,1] op_sel_hi:[1,1]
	v_exp_f32_e32 v204, v204
	v_pk_mul_f32 v[76:77], v[76:77], v[214:215] op_sel_hi:[1,0]
	v_pk_mul_f32 v[78:79], v[78:79], v[214:215] op_sel_hi:[1,0]
	v_pk_mul_f32 v[72:73], v[72:73], v[214:215] op_sel_hi:[1,0]
	v_exp_f32_e32 v205, v205
	v_pk_mul_f32 v[74:75], v[74:75], v[214:215] op_sel_hi:[1,0]
	v_pk_fma_f32 v[218:219], v[52:53], v[76:77], v[56:57]
	v_pk_fma_f32 v[220:221], v[54:55], v[78:79], v[58:59]
	v_exp_f32_e32 v206, v206
	v_fmac_f32_dpp v218, v76, v48 row_ror:1 row_mask:0xf bank_mask:0xf
	v_fmac_f32_dpp v219, v77, v49 row_ror:1 row_mask:0xf bank_mask:0xf
	v_fmac_f32_dpp v220, v78, v50 row_ror:1 row_mask:0xf bank_mask:0xf
	v_exp_f32_e32 v207, v207
	v_fmac_f32_dpp v221, v79, v51 row_ror:1 row_mask:0xf bank_mask:0xf
	v_fmac_f32_dpp v218, v76, v44 row_ror:2 row_mask:0xf bank_mask:0xf
	v_fmac_f32_dpp v219, v77, v45 row_ror:2 row_mask:0xf bank_mask:0xf
	v_pk_add_f32 v[204:205], v[204:205], 1.0 op_sel_hi:[1,0]
	v_pk_add_f32 v[206:207], v[206:207], 1.0 op_sel_hi:[1,0]
	v_rcp_f32_e32 v204, v204
	v_fmac_f32_dpp v220, v78, v46 row_ror:2 row_mask:0xf bank_mask:0xf
	v_fmac_f32_dpp v221, v79, v47 row_ror:2 row_mask:0xf bank_mask:0xf
	v_fmac_f32_dpp v218, v248, v160 row_ror:8 row_mask:0xf bank_mask:0xf
	v_rcp_f32_e32 v205, v205
	v_fmac_f32_dpp v219, v249, v161 row_ror:8 row_mask:0xf bank_mask:0xf
	v_fmac_f32_dpp v220, v250, v162 row_ror:8 row_mask:0xf bank_mask:0xf
	v_fmac_f32_dpp v221, v251, v163 row_ror:8 row_mask:0xf bank_mask:0xf
	v_rcp_f32_e32 v206, v206
	v_fmac_f32_dpp v218, v248, v164 row_ror:6 row_mask:0xf bank_mask:0xf
	v_fmac_f32_dpp v219, v249, v165 row_ror:6 row_mask:0xf bank_mask:0xf
	v_fmac_f32_dpp v220, v250, v166 row_ror:6 row_mask:0xf bank_mask:0xf
	v_rcp_f32_e32 v207, v207
	v_fmac_f32_dpp v221, v251, v167 row_ror:6 row_mask:0xf bank_mask:0xf
	v_pk_mul_f32 v[222:223], v[222:223], v[204:205]
	v_pk_mul_f32 v[224:225], v[224:225], v[206:207]
	v_pk_mul_f32 v[80:81], v[80:81], v[222:223]
	v_pk_mul_f32 v[82:83], v[82:83], v[224:225]
	v_cvt_pk_bf16_f32 v80, v80, v81
	v_cvt_pk_bf16_f32 v81, v82, v83
	s_and_saveexec_b64 s[28:29], s[74:75]
	global_store_dwordx2 v213, v[80:81], s[46:47]
	s_mov_b64 exec, s[28:29]
	s_add_u32 s46, s54, 0xfffea000
	s_addc_u32 s47, s55, -1
	v_pk_mul_f32 v[204:205], v[218:219], v[184:185] op_sel:[0,1] op_sel_hi:[1,1]
	v_pk_mul_f32 v[206:207], v[220:221], v[184:185] op_sel:[0,1] op_sel_hi:[1,1]
	v_exp_f32_e32 v204, v204
	v_pk_mul_f32 v[68:69], v[68:69], v[210:211] op_sel_hi:[1,0]
	v_pk_mul_f32 v[70:71], v[70:71], v[210:211] op_sel_hi:[1,0]
	v_pk_mul_f32 v[64:65], v[64:65], v[210:211] op_sel_hi:[1,0]
	v_exp_f32_e32 v205, v205
	v_pk_mul_f32 v[66:67], v[66:67], v[210:211] op_sel_hi:[1,0]
	v_pk_fma_f32 v[222:223], v[52:53], v[68:69], v[56:57]
; #define LAS __attribute__((address_space(3)))
; DI u32x2 pk4(f32x4 v) { u32x2 r; r.x = pk2(v[0], v[1]); r.y = pk2(v[2], v[3]); return r; }
;     DI void operator()(const AccT& acc, const Unit& u, int wr, int wc, int fr, int fq, LAS unsigned char* ldsx) const {
;     ...
;                 if (prompt) {
;                     if (ai | wr) { const int sai = wr ? ai : ai - 1, swr = wr ^ 1; const LAS float* hp = H + ((sai * 2 + swr) * 4 + wc) * 64 + 16 * n + 4 * fq;
;                         hm2 = *(const LAS f32x4*)hp; hm1 = *(const LAS f32x4*)(hp + 32); }
;                 } else { hm2 = *(const f32x4*)(state + (size_t)(sb * 2) * DFF + f); hm1 = *(const f32x4*)(state + (size_t)(sb * 2 + 1) * DFF + f); }
;                 f32x4 p1 = hm1, p2;
; #pragma unroll
;                 for (int j = 0; j < 4; ++j) p2[j] = fr == 1 ? hm1[j] : hm2[j];
; #pragma unroll
;                 for (int m = 0; m < 4; ++m) {
;                     const f32x4 g = acc[ai][0][m][n] * rs[ai][m];
;                     f32x4 gm1, gm2;
; #pragma unroll
;                     for (int j = 0; j < 4; ++j) {
;                         gm1[j] = __int_as_float(__builtin_amdgcn_update_dpp(__float_as_int(p1[j]), __float_as_int(g[j]), 0x111, 0xf, 0xf, false));
;                         gm2[j] = __int_as_float(__builtin_amdgcn_update_dpp(__float_as_int(p2[j]), __float_as_int(g[j]), 0x112, 0xf, 0xf, false));
;                         if (m < 3) {
;                             p1[j] = __int_as_float(__builtin_amdgcn_update_dpp(0, __float_as_int(g[j]), 0x121, 0xf, 0xf, false));
;                             p2[j] = __int_as_float(__builtin_amdgcn_update_dpp(0, __float_as_int(g[j]), 0x122, 0xf, 0xf, false)); }
;                     }
;                     const f32x4 cv = cb[n] + w0[n] * gm2 + w1[n] * gm1 + w2[n] * g;
;                     const f32x4 up = acc[ai][1][m][n] * rs[ai][m];
;                     f32x4 y;
; #pragma unroll
;                     for (int j = 0; j < 4; ++j) y[j] = cv[j] * __builtin_amdgcn_rcpf(1.f + __builtin_amdgcn_exp2f(-cv[j] * LOG2E)) * up[j];
;                     const int tok = tok0 + 128 * ai + 16 * m;
;                     bool ok = true;
;                     if (prompt && ai == 0 && m == 0) ok = (64 * wr + fr) >= 2;
;                     if (lastT) ok = ok && tok < SEQ;
;                     if (ok) *(u32x2*)(Y + ((unsigned)tok * (unsigned)DFF + (unsigned)f)) = pk4(y);
	v_pk_fma_f32 v[224:225], v[54:55], v[70:71], v[58:59]
	v_exp_f32_e32 v206, v206
	v_fmac_f32_dpp v222, v68, v48 row_ror:1 row_mask:0xf bank_mask:0xf
	v_fmac_f32_dpp v223, v69, v49 row_ror:1 row_mask:0xf bank_mask:0xf
	v_fmac_f32_dpp v224, v70, v50 row_ror:1 row_mask:0xf bank_mask:0xf
	v_exp_f32_e32 v207, v207
	v_fmac_f32_dpp v225, v71, v51 row_ror:1 row_mask:0xf bank_mask:0xf
	v_fmac_f32_dpp v222, v68, v44 row_ror:2 row_mask:0xf bank_mask:0xf
	v_fmac_f32_dpp v223, v69, v45 row_ror:2 row_mask:0xf bank_mask:0xf
	v_pk_add_f32 v[204:205], v[204:205], 1.0 op_sel_hi:[1,0]
	v_pk_add_f32 v[206:207], v[206:207], 1.0 op_sel_hi:[1,0]
	v_rcp_f32_e32 v204, v204
	v_fmac_f32_dpp v224, v70, v46 row_ror:2 row_mask:0xf bank_mask:0xf
	v_fmac_f32_dpp v225, v71, v47 row_ror:2 row_mask:0xf bank_mask:0xf
	v_fmac_f32_dpp v222, v76, v160 row_ror:1 row_mask:0xf bank_mask:0xf
	v_rcp_f32_e32 v205, v205
	v_fmac_f32_dpp v223, v77, v161 row_ror:1 row_mask:0xf bank_mask:0xf
	v_fmac_f32_dpp v224, v78, v162 row_ror:1 row_mask:0xf bank_mask:0xf
	v_fmac_f32_dpp v225, v79, v163 row_ror:1 row_mask:0xf bank_mask:0xf
	v_rcp_f32_e32 v206, v206
	v_fmac_f32_dpp v222, v76, v164 row_ror:2 row_mask:0xf bank_mask:0xf
	v_fmac_f32_dpp v223, v77, v165 row_ror:2 row_mask:0xf bank_mask:0xf
	v_fmac_f32_dpp v224, v78, v166 row_ror:2 row_mask:0xf bank_mask:0xf
	v_rcp_f32_e32 v207, v207
	v_fmac_f32_dpp v225, v79, v167 row_ror:2 row_mask:0xf bank_mask:0xf
	v_pk_mul_f32 v[218:219], v[218:219], v[204:205]
	v_pk_mul_f32 v[220:221], v[220:221], v[206:207]
	v_pk_mul_f32 v[72:73], v[72:73], v[218:219]
	v_pk_mul_f32 v[74:75], v[74:75], v[220:221]
	v_cvt_pk_bf16_f32 v72, v72, v73
	v_cvt_pk_bf16_f32 v73, v74, v75
	s_and_saveexec_b64 s[28:29], s[60:61]
	global_store_dwordx2 v213, v[72:73], s[46:47] offset:32
	s_mov_b64 exec, s[28:29]
	s_add_u32 s46, s46, 0x16000
	s_addc_u32 s47, s47, 0
	v_pk_mul_f32 v[204:205], v[222:223], v[184:185] op_sel:[0,1] op_sel_hi:[1,1]
	v_pk_mul_f32 v[206:207], v[224:225], v[184:185] op_sel:[0,1] op_sel_hi:[1,1]
	v_exp_f32_e32 v204, v204
	v_pk_mul_f32 v[60:61], v[60:61], v[208:209] op_sel_hi:[1,0]
	v_pk_mul_f32 v[62:63], v[62:63], v[208:209] op_sel_hi:[1,0]
	v_pk_mul_f32 v[40:41], v[40:41], v[208:209] op_sel_hi:[1,0]
	v_exp_f32_e32 v205, v205
	v_pk_mul_f32 v[42:43], v[42:43], v[208:209] op_sel_hi:[1,0]
	v_pk_fma_f32 v[218:219], v[52:53], v[60:61], v[56:57]
	v_pk_fma_f32 v[220:221], v[54:55], v[62:63], v[58:59]
	v_exp_f32_e32 v206, v206
	v_fmac_f32_dpp v218, v60, v48 row_ror:1 row_mask:0xf bank_mask:0xf
	v_fmac_f32_dpp v219, v61, v49 row_ror:1 row_mask:0xf bank_mask:0xf
	v_fmac_f32_dpp v220, v62, v50 row_ror:1 row_mask:0xf bank_mask:0xf
	v_exp_f32_e32 v207, v207
	v_fmac_f32_dpp v221, v63, v51 row_ror:1 row_mask:0xf bank_mask:0xf
	v_fmac_f32_dpp v218, v60, v44 row_ror:2 row_mask:0xf bank_mask:0xf
	v_fmac_f32_dpp v219, v61, v45 row_ror:2 row_mask:0xf bank_mask:0xf
	v_pk_add_f32 v[204:205], v[204:205], 1.0 op_sel_hi:[1,0]
	v_pk_add_f32 v[206:207], v[206:207], 1.0 op_sel_hi:[1,0]
	v_rcp_f32_e32 v204, v204
	v_fmac_f32_dpp v220, v62, v46 row_ror:2 row_mask:0xf bank_mask:0xf
	v_fmac_f32_dpp v221, v63, v47 row_ror:2 row_mask:0xf bank_mask:0xf
	v_fmac_f32_dpp v218, v68, v160 row_ror:1 row_mask:0xf bank_mask:0xf
	v_rcp_f32_e32 v205, v205
	v_fmac_f32_dpp v219, v69, v161 row_ror:1 row_mask:0xf bank_mask:0xf
	v_fmac_f32_dpp v220, v70, v162 row_ror:1 row_mask:0xf bank_mask:0xf
	v_fmac_f32_dpp v221, v71, v163 row_ror:1 row_mask:0xf bank_mask:0xf
	v_rcp_f32_e32 v206, v206
	v_fmac_f32_dpp v218, v68, v164 row_ror:2 row_mask:0xf bank_mask:0xf
	v_fmac_f32_dpp v219, v69, v165 row_ror:2 row_mask:0xf bank_mask:0xf
	v_fmac_f32_dpp v220, v70, v166 row_ror:2 row_mask:0xf bank_mask:0xf
	v_rcp_f32_e32 v207, v207
	v_fmac_f32_dpp v221, v71, v167 row_ror:2 row_mask:0xf bank_mask:0xf
	v_pk_mul_f32 v[222:223], v[222:223], v[204:205]
	v_pk_mul_f32 v[224:225], v[224:225], v[206:207]
	v_pk_mul_f32 v[64:65], v[64:65], v[222:223]
	v_pk_mul_f32 v[66:67], v[66:67], v[224:225]
	v_cvt_pk_bf16_f32 v64, v64, v65
	v_cvt_pk_bf16_f32 v65, v66, v67
	s_and_saveexec_b64 s[28:29], s[62:63]
	global_store_dwordx2 v213, v[64:65], s[46:47] offset:32
	s_mov_b64 exec, s[28:29]
	s_add_u32 s46, s46, 0x16000
	s_addc_u32 s47, s47, 0
	v_pk_mul_f32 v[204:205], v[218:219], v[184:185] op_sel:[0,1] op_sel_hi:[1,1]
	v_pk_mul_f32 v[206:207], v[220:221], v[184:185] op_sel:[0,1] op_sel_hi:[1,1]
	v_exp_f32_e32 v204, v204
	v_pk_mul_f32 v[36:37], v[36:37], v[202:203] op_sel_hi:[1,0]
	v_pk_mul_f32 v[38:39], v[38:39], v[202:203] op_sel_hi:[1,0]
	v_pk_mul_f32 v[32:33], v[32:33], v[202:203] op_sel_hi:[1,0]
	v_exp_f32_e32 v205, v205
	v_pk_mul_f32 v[34:35], v[34:35], v[202:203] op_sel_hi:[1,0]
	v_pk_fma_f32 v[222:223], v[52:53], v[36:37], v[56:57]
	v_pk_fma_f32 v[224:225], v[54:55], v[38:39], v[58:59]
	v_exp_f32_e32 v206, v206
	v_fmac_f32_dpp v222, v36, v48 row_ror:1 row_mask:0xf bank_mask:0xf
	v_fmac_f32_dpp v223, v37, v49 row_ror:1 row_mask:0xf bank_mask:0xf
	v_fmac_f32_dpp v224, v38, v50 row_ror:1 row_mask:0xf bank_mask:0xf
	v_exp_f32_e32 v207, v207
	v_fmac_f32_dpp v225, v39, v51 row_ror:1 row_mask:0xf bank_mask:0xf
	v_fmac_f32_dpp v222, v36, v44 row_ror:2 row_mask:0xf bank_mask:0xf
	v_fmac_f32_dpp v223, v37, v45 row_ror:2 row_mask:0xf bank_mask:0xf
	v_pk_add_f32 v[204:205], v[204:205], 1.0 op_sel_hi:[1,0]
	v_pk_add_f32 v[206:207], v[206:207], 1.0 op_sel_hi:[1,0]
	v_rcp_f32_e32 v204, v204
	v_fmac_f32_dpp v224, v38, v46 row_ror:2 row_mask:0xf bank_mask:0xf
	v_fmac_f32_dpp v225, v39, v47 row_ror:2 row_mask:0xf bank_mask:0xf
	v_fmac_f32_dpp v222, v60, v160 row_ror:1 row_mask:0xf bank_mask:0xf
	v_rcp_f32_e32 v205, v205
; #define LAS __attribute__((address_space(3)))
; DI u32x2 pk4(f32x4 v) { u32x2 r; r.x = pk2(v[0], v[1]); r.y = pk2(v[2], v[3]); return r; }
;     DI void operator()(const AccT& acc, const Unit& u, int wr, int wc, int fr, int fq, LAS unsigned char* ldsx) const {
;     ...
;                 if (prompt) {
;                     if (ai | wr) { const int sai = wr ? ai : ai - 1, swr = wr ^ 1; const LAS float* hp = H + ((sai * 2 + swr) * 4 + wc) * 64 + 16 * n + 4 * fq;
;                         hm2 = *(const LAS f32x4*)hp; hm1 = *(const LAS f32x4*)(hp + 32); }
;                 } else { hm2 = *(const f32x4*)(state + (size_t)(sb * 2) * DFF + f); hm1 = *(const f32x4*)(state + (size_t)(sb * 2 + 1) * DFF + f); }
;                 f32x4 p1 = hm1, p2;
; #pragma unroll
;                 for (int j = 0; j < 4; ++j) p2[j] = fr == 1 ? hm1[j] : hm2[j];
; #pragma unroll
;                 for (int m = 0; m < 4; ++m) {
;                     const f32x4 g = acc[ai][0][m][n] * rs[ai][m];
;                     f32x4 gm1, gm2;
; #pragma unroll
;                     for (int j = 0; j < 4; ++j) {
;                         gm1[j] = __int_as_float(__builtin_amdgcn_update_dpp(__float_as_int(p1[j]), __float_as_int(g[j]), 0x111, 0xf, 0xf, false));
;                         gm2[j] = __int_as_float(__builtin_amdgcn_update_dpp(__float_as_int(p2[j]), __float_as_int(g[j]), 0x112, 0xf, 0xf, false));
;                         if (m < 3) {
;                             p1[j] = __int_as_float(__builtin_amdgcn_update_dpp(0, __float_as_int(g[j]), 0x121, 0xf, 0xf, false));
;                             p2[j] = __int_as_float(__builtin_amdgcn_update_dpp(0, __float_as_int(g[j]), 0x122, 0xf, 0xf, false)); }
;                     }
;                     const f32x4 cv = cb[n] + w0[n] * gm2 + w1[n] * gm1 + w2[n] * g;
;                     const f32x4 up = acc[ai][1][m][n] * rs[ai][m];
;                     f32x4 y;
; #pragma unroll
;                     for (int j = 0; j < 4; ++j) y[j] = cv[j] * __builtin_amdgcn_rcpf(1.f + __builtin_amdgcn_exp2f(-cv[j] * LOG2E)) * up[j];
;                     const int tok = tok0 + 128 * ai + 16 * m;
;                     bool ok = true;
;                     if (prompt && ai == 0 && m == 0) ok = (64 * wr + fr) >= 2;
;                     if (lastT) ok = ok && tok < SEQ;
;                     if (ok) *(u32x2*)(Y + ((unsigned)tok * (unsigned)DFF + (unsigned)f)) = pk4(y);
	v_fmac_f32_dpp v223, v61, v161 row_ror:1 row_mask:0xf bank_mask:0xf
	v_fmac_f32_dpp v224, v62, v162 row_ror:1 row_mask:0xf bank_mask:0xf
	v_fmac_f32_dpp v225, v63, v163 row_ror:1 row_mask:0xf bank_mask:0xf
	v_rcp_f32_e32 v206, v206
	v_fmac_f32_dpp v222, v60, v164 row_ror:2 row_mask:0xf bank_mask:0xf
	v_fmac_f32_dpp v223, v61, v165 row_ror:2 row_mask:0xf bank_mask:0xf
	v_fmac_f32_dpp v224, v62, v166 row_ror:2 row_mask:0xf bank_mask:0xf
	v_rcp_f32_e32 v207, v207
	v_fmac_f32_dpp v225, v63, v167 row_ror:2 row_mask:0xf bank_mask:0xf
	v_pk_mul_f32 v[218:219], v[218:219], v[204:205]
	v_pk_mul_f32 v[220:221], v[220:221], v[206:207]
	v_pk_mul_f32 v[40:41], v[40:41], v[218:219]
	v_pk_mul_f32 v[42:43], v[42:43], v[220:221]
	v_cvt_pk_bf16_f32 v40, v40, v41
	v_cvt_pk_bf16_f32 v41, v42, v43
	s_and_saveexec_b64 s[28:29], s[64:65]
	global_store_dwordx2 v213, v[40:41], s[46:47] offset:32
	s_mov_b64 exec, s[28:29]
	s_add_u32 s46, s46, 0x16000
	s_addc_u32 s47, s47, 0
	v_pk_mul_f32 v[204:205], v[222:223], v[184:185] op_sel:[0,1] op_sel_hi:[1,1]
	v_pk_mul_f32 v[206:207], v[224:225], v[184:185] op_sel:[0,1] op_sel_hi:[1,1]
	v_exp_f32_e32 v204, v204
	v_pk_mul_f32 v[28:29], v[28:29], v[200:201] op_sel_hi:[1,0]
	v_pk_mul_f32 v[30:31], v[30:31], v[200:201] op_sel_hi:[1,0]
	v_pk_mul_f32 v[24:25], v[24:25], v[200:201] op_sel_hi:[1,0]
	v_exp_f32_e32 v205, v205
	v_pk_mul_f32 v[26:27], v[26:27], v[200:201] op_sel_hi:[1,0]
	v_pk_fma_f32 v[218:219], v[52:53], v[28:29], v[56:57]
	v_pk_fma_f32 v[220:221], v[54:55], v[30:31], v[58:59]
	v_exp_f32_e32 v206, v206
	v_fmac_f32_dpp v218, v28, v48 row_ror:1 row_mask:0xf bank_mask:0xf
	v_fmac_f32_dpp v219, v29, v49 row_ror:1 row_mask:0xf bank_mask:0xf
	v_fmac_f32_dpp v220, v30, v50 row_ror:1 row_mask:0xf bank_mask:0xf
	v_exp_f32_e32 v207, v207
	v_fmac_f32_dpp v221, v31, v51 row_ror:1 row_mask:0xf bank_mask:0xf
	v_fmac_f32_dpp v218, v28, v44 row_ror:2 row_mask:0xf bank_mask:0xf
	v_fmac_f32_dpp v219, v29, v45 row_ror:2 row_mask:0xf bank_mask:0xf
	v_pk_add_f32 v[204:205], v[204:205], 1.0 op_sel_hi:[1,0]
	v_pk_add_f32 v[206:207], v[206:207], 1.0 op_sel_hi:[1,0]
	v_rcp_f32_e32 v204, v204
	v_fmac_f32_dpp v220, v30, v46 row_ror:2 row_mask:0xf bank_mask:0xf
	v_fmac_f32_dpp v221, v31, v47 row_ror:2 row_mask:0xf bank_mask:0xf
	v_fmac_f32_dpp v218, v248, v160 row_ror:4 row_mask:0xf bank_mask:0xf
	v_rcp_f32_e32 v205, v205
	v_fmac_f32_dpp v219, v249, v161 row_ror:4 row_mask:0xf bank_mask:0xf
	v_fmac_f32_dpp v220, v250, v162 row_ror:4 row_mask:0xf bank_mask:0xf
	v_fmac_f32_dpp v221, v251, v163 row_ror:4 row_mask:0xf bank_mask:0xf
	v_rcp_f32_e32 v206, v206
	v_fmac_f32_dpp v218, v248, v164 row_ror:2 row_mask:0xf bank_mask:0xf
	v_fmac_f32_dpp v219, v249, v165 row_ror:2 row_mask:0xf bank_mask:0xf
	v_fmac_f32_dpp v220, v250, v166 row_ror:2 row_mask:0xf bank_mask:0xf
	v_rcp_f32_e32 v207, v207
	v_fmac_f32_dpp v221, v251, v167 row_ror:2 row_mask:0xf bank_mask:0xf
	v_pk_mul_f32 v[222:223], v[222:223], v[204:205]
	v_pk_mul_f32 v[224:225], v[224:225], v[206:207]
	v_pk_mul_f32 v[32:33], v[32:33], v[222:223]
	v_pk_mul_f32 v[34:35], v[34:35], v[224:225]
	v_cvt_pk_bf16_f32 v32, v32, v33
	v_cvt_pk_bf16_f32 v33, v34, v35
	s_and_saveexec_b64 s[28:29], s[66:67]
	global_store_dwordx2 v213, v[32:33], s[46:47] offset:32
	s_mov_b64 exec, s[28:29]
	s_add_u32 s46, s46, 0x6e000
	s_addc_u32 s47, s47, 0
	v_pk_mul_f32 v[204:205], v[218:219], v[184:185] op_sel:[0,1] op_sel_hi:[1,1]
	v_pk_mul_f32 v[206:207], v[220:221], v[184:185] op_sel:[0,1] op_sel_hi:[1,1]
	v_exp_f32_e32 v204, v204
	v_pk_mul_f32 v[20:21], v[20:21], v[192:193] op_sel_hi:[1,0]
	v_pk_mul_f32 v[22:23], v[22:23], v[192:193] op_sel_hi:[1,0]
	v_pk_mul_f32 v[16:17], v[16:17], v[192:193] op_sel_hi:[1,0]
	v_exp_f32_e32 v205, v205
	v_pk_mul_f32 v[18:19], v[18:19], v[192:193] op_sel_hi:[1,0]
	v_pk_fma_f32 v[222:223], v[52:53], v[20:21], v[56:57]
	v_pk_fma_f32 v[224:225], v[54:55], v[22:23], v[58:59]
	v_exp_f32_e32 v206, v206
	v_fmac_f32_dpp v222, v20, v48 row_ror:1 row_mask:0xf bank_mask:0xf
	v_fmac_f32_dpp v223, v21, v49 row_ror:1 row_mask:0xf bank_mask:0xf
	v_fmac_f32_dpp v224, v22, v50 row_ror:1 row_mask:0xf bank_mask:0xf
	v_exp_f32_e32 v207, v207
	v_fmac_f32_dpp v225, v23, v51 row_ror:1 row_mask:0xf bank_mask:0xf
	v_fmac_f32_dpp v222, v20, v44 row_ror:2 row_mask:0xf bank_mask:0xf
	v_fmac_f32_dpp v223, v21, v45 row_ror:2 row_mask:0xf bank_mask:0xf
	v_pk_add_f32 v[204:205], v[204:205], 1.0 op_sel_hi:[1,0]
	v_pk_add_f32 v[206:207], v[206:207], 1.0 op_sel_hi:[1,0]
	v_rcp_f32_e32 v204, v204
	v_fmac_f32_dpp v224, v22, v46 row_ror:2 row_mask:0xf bank_mask:0xf
	v_fmac_f32_dpp v225, v23, v47 row_ror:2 row_mask:0xf bank_mask:0xf
	v_fmac_f32_dpp v222, v28, v160 row_ror:1 row_mask:0xf bank_mask:0xf
	v_rcp_f32_e32 v205, v205
	v_fmac_f32_dpp v223, v29, v161 row_ror:1 row_mask:0xf bank_mask:0xf
	v_fmac_f32_dpp v224, v30, v162 row_ror:1 row_mask:0xf bank_mask:0xf
	v_fmac_f32_dpp v225, v31, v163 row_ror:1 row_mask:0xf bank_mask:0xf
	v_rcp_f32_e32 v206, v206
	v_fmac_f32_dpp v222, v28, v164 row_ror:2 row_mask:0xf bank_mask:0xf
	v_fmac_f32_dpp v223, v29, v165 row_ror:2 row_mask:0xf bank_mask:0xf
	v_fmac_f32_dpp v224, v30, v166 row_ror:2 row_mask:0xf bank_mask:0xf
	v_rcp_f32_e32 v207, v207
	v_fmac_f32_dpp v225, v31, v167 row_ror:2 row_mask:0xf bank_mask:0xf
	v_pk_mul_f32 v[218:219], v[218:219], v[204:205]
	v_pk_mul_f32 v[220:221], v[220:221], v[206:207]
	v_pk_mul_f32 v[24:25], v[24:25], v[218:219]
	v_pk_mul_f32 v[26:27], v[26:27], v[220:221]
	v_cvt_pk_bf16_f32 v24, v24, v25
	v_cvt_pk_bf16_f32 v25, v26, v27
	s_and_saveexec_b64 s[28:29], s[68:69]
	global_store_dwordx2 v213, v[24:25], s[46:47] offset:32
	s_mov_b64 exec, s[28:29]
;     DI void operator()(const AccT& acc, const Unit& u, int wr, int wc, int fr, int fq, LAS unsigned char* ldsx) const {
;     ...
;                 if (prompt) {
;                     if (ai | wr) { const int sai = wr ? ai : ai - 1, swr = wr ^ 1; const LAS float* hp = H + ((sai * 2 + swr) * 4 + wc) * 64 + 16 * n + 4 * fq;
;                         hm2 = *(const LAS f32x4*)hp; hm1 = *(const LAS f32x4*)(hp + 32); }
;                 } else { hm2 = *(const f32x4*)(state + (size_t)(sb * 2) * DFF + f); hm1 = *(const f32x4*)(state + (size_t)(sb * 2 + 1) * DFF + f); }
;                 f32x4 p1 = hm1, p2;
; #pragma unroll
;                 for (int j = 0; j < 4; ++j) p2[j] = fr == 1 ? hm1[j] : hm2[j];
; #pragma unroll
;                 for (int m = 0; m < 4; ++m) {
;                     const f32x4 g = acc[ai][0][m][n] * rs[ai][m];
;                     f32x4 gm1, gm2;
; #pragma unroll
;                     for (int j = 0; j < 4; ++j) {
;                         gm1[j] = __int_as_float(__builtin_amdgcn_update_dpp(__float_as_int(p1[j]), __float_as_int(g[j]), 0x111, 0xf, 0xf, false));
;                         gm2[j] = __int_as_float(__builtin_amdgcn_update_dpp(__float_as_int(p2[j]), __float_as_int(g[j]), 0x112, 0xf, 0xf, false));
;                         if (m < 3) {
;                             p1[j] = __int_as_float(__builtin_amdgcn_update_dpp(0, __float_as_int(g[j]), 0x121, 0xf, 0xf, false));
;                             p2[j] = __int_as_float(__builtin_amdgcn_update_dpp(0, __float_as_int(g[j]), 0x122, 0xf, 0xf, false)); }
;                     }
;                     const f32x4 cv = cb[n] + w0[n] * gm2 + w1[n] * gm1 + w2[n] * g;
;                     const f32x4 up = acc[ai][1][m][n] * rs[ai][m];
;                     f32x4 y;
; #pragma unroll
;                     for (int j = 0; j < 4; ++j) y[j] = cv[j] * __builtin_amdgcn_rcpf(1.f + __builtin_amdgcn_exp2f(-cv[j] * LOG2E)) * up[j];
;                     const int tok = tok0 + 128 * ai + 16 * m;
;                     bool ok = true;
;                     if (prompt && ai == 0 && m == 0) ok = (64 * wr + fr) >= 2;
;                     if (lastT) ok = ok && tok < SEQ;
;                     if (ok) *(u32x2*)(Y + ((unsigned)tok * (unsigned)DFF + (unsigned)f)) = pk4(y);
;                     if (lastT) { if (tok == SEQ - 2 || tok == SEQ - 1) *(f32x4*)(out + OFF_CVP + (size_t)(tok - (SEQ - 2)) * DFF + f) = g; }
	s_add_u32 s46, s46, 0x16000
	s_addc_u32 s47, s47, 0
	v_pk_mul_f32 v[204:205], v[222:223], v[184:185] op_sel:[0,1] op_sel_hi:[1,1]
	v_pk_mul_f32 v[206:207], v[224:225], v[184:185] op_sel:[0,1] op_sel_hi:[1,1]
	v_exp_f32_e32 v204, v204
	v_pk_mul_f32 v[12:13], v[12:13], v[190:191] op_sel_hi:[1,0]
	v_pk_mul_f32 v[14:15], v[14:15], v[190:191] op_sel_hi:[1,0]
	v_pk_mul_f32 v[8:9], v[8:9], v[190:191] op_sel_hi:[1,0]
	v_exp_f32_e32 v205, v205
	v_pk_mul_f32 v[10:11], v[10:11], v[190:191] op_sel_hi:[1,0]
	v_pk_fma_f32 v[218:219], v[52:53], v[12:13], v[56:57]
	v_pk_fma_f32 v[220:221], v[54:55], v[14:15], v[58:59]
	v_exp_f32_e32 v206, v206
	v_fmac_f32_dpp v218, v12, v48 row_ror:1 row_mask:0xf bank_mask:0xf
	v_fmac_f32_dpp v219, v13, v49 row_ror:1 row_mask:0xf bank_mask:0xf
	v_fmac_f32_dpp v220, v14, v50 row_ror:1 row_mask:0xf bank_mask:0xf
	v_exp_f32_e32 v207, v207
	v_fmac_f32_dpp v221, v15, v51 row_ror:1 row_mask:0xf bank_mask:0xf
	v_fmac_f32_dpp v218, v12, v44 row_ror:2 row_mask:0xf bank_mask:0xf
	v_fmac_f32_dpp v219, v13, v45 row_ror:2 row_mask:0xf bank_mask:0xf
	v_pk_add_f32 v[204:205], v[204:205], 1.0 op_sel_hi:[1,0]
	v_pk_add_f32 v[206:207], v[206:207], 1.0 op_sel_hi:[1,0]
	v_rcp_f32_e32 v204, v204
	v_fmac_f32_dpp v220, v14, v46 row_ror:2 row_mask:0xf bank_mask:0xf
	v_fmac_f32_dpp v221, v15, v47 row_ror:2 row_mask:0xf bank_mask:0xf
	v_fmac_f32_dpp v218, v20, v160 row_ror:1 row_mask:0xf bank_mask:0xf
	v_rcp_f32_e32 v205, v205
	v_fmac_f32_dpp v219, v21, v161 row_ror:1 row_mask:0xf bank_mask:0xf
	v_fmac_f32_dpp v220, v22, v162 row_ror:1 row_mask:0xf bank_mask:0xf
	v_fmac_f32_dpp v221, v23, v163 row_ror:1 row_mask:0xf bank_mask:0xf
	v_rcp_f32_e32 v206, v206
	v_fmac_f32_dpp v218, v20, v164 row_ror:2 row_mask:0xf bank_mask:0xf
	v_fmac_f32_dpp v219, v21, v165 row_ror:2 row_mask:0xf bank_mask:0xf
	v_fmac_f32_dpp v220, v22, v166 row_ror:2 row_mask:0xf bank_mask:0xf
	v_rcp_f32_e32 v207, v207
	v_fmac_f32_dpp v221, v23, v167 row_ror:2 row_mask:0xf bank_mask:0xf
	v_pk_mul_f32 v[222:223], v[222:223], v[204:205]
	v_pk_mul_f32 v[224:225], v[224:225], v[206:207]
	v_pk_mul_f32 v[16:17], v[16:17], v[222:223]
	v_pk_mul_f32 v[18:19], v[18:19], v[224:225]
	v_cvt_pk_bf16_f32 v16, v16, v17
	v_cvt_pk_bf16_f32 v17, v18, v19
	s_and_saveexec_b64 s[28:29], s[70:71]
	global_store_dwordx2 v213, v[16:17], s[46:47] offset:32
	s_mov_b64 exec, s[28:29]
	s_add_u32 s46, s46, 0x16000
	s_addc_u32 s47, s47, 0
	v_pk_mul_f32 v[204:205], v[218:219], v[184:185] op_sel:[0,1] op_sel_hi:[1,1]
	v_pk_mul_f32 v[206:207], v[220:221], v[184:185] op_sel:[0,1] op_sel_hi:[1,1]
	v_exp_f32_e32 v204, v204
	v_pk_mul_f32 v[4:5], v[4:5], v[184:185] op_sel_hi:[1,0]
	v_pk_mul_f32 v[6:7], v[6:7], v[184:185] op_sel_hi:[1,0]
	v_pk_mul_f32 v[0:1], v[0:1], v[184:185] op_sel_hi:[1,0]
	v_exp_f32_e32 v205, v205
	v_pk_mul_f32 v[2:3], v[2:3], v[184:185] op_sel_hi:[1,0]
	v_pk_fma_f32 v[222:223], v[52:53], v[4:5], v[56:57]
	v_pk_fma_f32 v[224:225], v[54:55], v[6:7], v[58:59]
	v_exp_f32_e32 v206, v206
	v_fmac_f32_dpp v222, v4, v48 row_ror:1 row_mask:0xf bank_mask:0xf
	v_fmac_f32_dpp v223, v5, v49 row_ror:1 row_mask:0xf bank_mask:0xf
	v_fmac_f32_dpp v224, v6, v50 row_ror:1 row_mask:0xf bank_mask:0xf
	v_exp_f32_e32 v207, v207
	v_fmac_f32_dpp v225, v7, v51 row_ror:1 row_mask:0xf bank_mask:0xf
	v_fmac_f32_dpp v222, v4, v44 row_ror:2 row_mask:0xf bank_mask:0xf
	v_fmac_f32_dpp v223, v5, v45 row_ror:2 row_mask:0xf bank_mask:0xf
	v_pk_add_f32 v[204:205], v[204:205], 1.0 op_sel_hi:[1,0]
	v_pk_add_f32 v[206:207], v[206:207], 1.0 op_sel_hi:[1,0]
	v_rcp_f32_e32 v204, v204
	v_fmac_f32_dpp v224, v6, v46 row_ror:2 row_mask:0xf bank_mask:0xf
	v_fmac_f32_dpp v225, v7, v47 row_ror:2 row_mask:0xf bank_mask:0xf
	v_fmac_f32_dpp v222, v12, v160 row_ror:1 row_mask:0xf bank_mask:0xf
	v_rcp_f32_e32 v205, v205
	v_fmac_f32_dpp v223, v13, v161 row_ror:1 row_mask:0xf bank_mask:0xf
	v_fmac_f32_dpp v224, v14, v162 row_ror:1 row_mask:0xf bank_mask:0xf
	v_fmac_f32_dpp v225, v15, v163 row_ror:1 row_mask:0xf bank_mask:0xf
	v_rcp_f32_e32 v206, v206
	v_fmac_f32_dpp v222, v12, v164 row_ror:2 row_mask:0xf bank_mask:0xf
	v_fmac_f32_dpp v223, v13, v165 row_ror:2 row_mask:0xf bank_mask:0xf
	v_fmac_f32_dpp v224, v14, v166 row_ror:2 row_mask:0xf bank_mask:0xf
	v_rcp_f32_e32 v207, v207
	v_fmac_f32_dpp v225, v15, v167 row_ror:2 row_mask:0xf bank_mask:0xf
	v_pk_mul_f32 v[218:219], v[218:219], v[204:205]
	v_pk_mul_f32 v[220:221], v[220:221], v[206:207]
	v_pk_mul_f32 v[8:9], v[8:9], v[218:219]
	v_pk_mul_f32 v[10:11], v[10:11], v[220:221]
	v_cvt_pk_bf16_f32 v8, v8, v9
	v_cvt_pk_bf16_f32 v9, v10, v11
	s_and_saveexec_b64 s[28:29], s[72:73]
	global_store_dwordx2 v213, v[8:9], s[46:47] offset:32
	s_mov_b64 exec, s[28:29]
	s_add_u32 s46, s46, 0x16000
	s_addc_u32 s47, s47, 0
	v_pk_mul_f32 v[204:205], v[222:223], v[184:185] op_sel:[0,1] op_sel_hi:[1,1]
	v_pk_mul_f32 v[206:207], v[224:225], v[184:185] op_sel:[0,1] op_sel_hi:[1,1]
	v_exp_f32_e32 v204, v204
	v_exp_f32_e32 v205, v205
	v_exp_f32_e32 v206, v206
	v_exp_f32_e32 v207, v207
	v_pk_add_f32 v[204:205], v[204:205], 1.0 op_sel_hi:[1,0]
	v_pk_add_f32 v[206:207], v[206:207], 1.0 op_sel_hi:[1,0]
	v_rcp_f32_e32 v204, v204
	v_rcp_f32_e32 v205, v205
	v_rcp_f32_e32 v206, v206
	v_rcp_f32_e32 v207, v207
	v_pk_mul_f32 v[222:223], v[222:223], v[204:205]
	v_pk_mul_f32 v[224:225], v[224:225], v[206:207]
	v_pk_mul_f32 v[0:1], v[0:1], v[222:223]
	v_pk_mul_f32 v[2:3], v[2:3], v[224:225]
	v_cvt_pk_bf16_f32 v0, v0, v1
	v_cvt_pk_bf16_f32 v1, v2, v3
	s_and_saveexec_b64 s[28:29], s[74:75]
	global_store_dwordx2 v213, v[0:1], s[46:47] offset:32
	s_mov_b64 exec, s[28:29]
	s_add_u32 s46, s54, 0xfffea000
	s_addc_u32 s47, s55, -1
	s_cmp_gt_i32 s42, 64
	s_cbranch_scc0 .Lgu_nocvs
	v_readlane_b32 s30, v252, 0
	v_readlane_b32 s31, v252, 1
	s_lshl_b32 s23, s42, 2
	s_add_i32 s23, s36, s23
	s_lshl_b32 s23, s23, 1
	s_movk_i32 s76, 0x2c00
	v_add_u32_e32 v186, s23, v233
	v_mad_i64_i32 v[186:187], s[34:35], v186, s76, 0
	v_lshl_add_u64 v[186:187], s[14:15], 0, v[186:187]
	v_lshl_add_u64 v[186:187], v[216:217], 2, v[186:187]
	s_and_saveexec_b64 s[28:29], s[30:31]
	global_store_dwordx4 v[186:187], v[116:119], off
	global_store_dwordx4 v[186:187], v[36:39], off offset:64
	s_mov_b64 exec, s[28:29]
	s_add_i32 s23, s23, 4
	v_add_u32_e32 v186, s23, v233
	v_mad_i64_i32 v[186:187], s[34:35], v186, s76, 0
	v_lshl_add_u64 v[186:187], s[14:15], 0, v[186:187]
	v_lshl_add_u64 v[186:187], v[216:217], 2, v[186:187]
	s_and_saveexec_b64 s[28:29], s[30:31]
	global_store_dwordx4 v[186:187], v[84:87], off
	global_store_dwordx4 v[186:187], v[4:7], off offset:64
	s_mov_b64 exec, s[28:29]
